# neighbourhood-attention tile loop: bias diamonds flattened to back-to-back reads + add + select against the -1e30 constant register, dead inits removed
# speedup vs baseline: 1.0063x; 1.0063x over previous
; DI void frag64_load(Frag64& f, const bf16_t* P, const bf16_t* vt, int b, int u, int kcol, int lane) {
; #pragma unroll
;   for (int i = 0; i < 4; ++i) {
;     f.k[i] = *(const u32x4*)(P + (size_t)rowOfU(b, u + (lane >> 3) + 8 * i) * NP + kcol + (lane & 7) * 8);
;     f.v[i] = *(const u32x4*)(vt + (size_t)((lane >> 2) + 16 * i) * UA + u + (lane & 3) * 8);
;   }
; }
; template <int MODE>
; DI void attn64_wave(const Params& p, int layer, int b, int hq, int qrow0, int t0, const float* rpb_lds, unsigned char* wlds) {
;     ...
;   auto tile_u = [&](int t) -> int {
;     if (t < 8) return 32 * t;
;     if (MODE == 0) return CTX + (rs + ((t - 8) >> 1)) * 64 + ((t - 8) & 1) * 32;
;     const int kt0 = t0 - 128 + 32 * (t - 8);
;     return CTX + min(max(kt0, 0), SEQ - 32);
;   };
;   auto load_tile = [&](Frag64& f, int t) { frag64_load(f, p.P, vt, b, tile_u(t), kcol, lane); };
;   unsigned char* Kw = wlds; unsigned char* Vw = wlds + W64_KB;
;   auto compute_tile = [&](const Frag64& f, int t) {
; #pragma unroll
;     for (int i = 0; i < 4; ++i) {
;       *(u32x4*)(Kw + ((lane >> 3) + 8 * i) * LDS_STRIDE + (lane & 7) * 16) = f.k[i];
;       *(u32x4*)(Vw + ((lane >> 2) + 16 * i) * W64_VSTR + (lane & 3) * 16) = f.v[i];
;     }
;     bf16x8 kf[4], vf[2][2];
; #pragma unroll
;     for (int ks = 0; ks < 4; ++ks) kf[ks] = __builtin_bit_cast(bf16x8, *(const u32x4*)(Kw + pr * LDS_STRIDE + (16 * ks + 8 * hh) * 2));
; #pragma unroll
;     for (int dh = 0; dh < 2; ++dh)
; #pragma unroll
;       for (int s2 = 0; s2 < 2; ++s2) vf[dh][s2] = __builtin_bit_cast(bf16x8, *(const u32x4*)(Vw + (32 * dh + qi) * W64_VSTR + (16 * s2 + 8 * hh) * 2));
;     f32x16 s;
; #pragma unroll
;     for (int i = 0; i < 16; ++i) s[i] = negM2;
; #pragma unroll
;     for (int ks = 0; ks < 4; ++ks) s = MFMA32(kf[ks], qf[ks], s);
;     float pe[16];
;     if (t < 8) {
; #pragma unroll
;       for (int i = 0; i < 16; ++i) pe[i] = fexp2(s[i]);
;     } else if (MODE == 0) {
;       const int kr = rs + ((t - 8) >> 1), hf = (t - 8) & 1;
;       const float* rrow = rpb + (kr - r + 7) * 31 + 15 - c;
; #pragma unroll
;       for (int i = 0; i < 16; ++i) {
;         const int kc = hf * 32 + 16 * (i >> 3) + 8 * hh + (i & 7);
;         const bool valid = (kc >= ws) && (kc < ws + 16);
;         const int kcc = min(max(kc, ws), ws + 15);
;         pe[i] = fexp2(valid ? s[i] + rrow[kcc] : -1e30f);
;       }
.LBB0_341:
	v_add_u32_e32 v126, v192, v134
	s_movk_i32 s30, 0x100
	v_mov_b32_e32 v127, s22
	v_mov_b32_e32 v143, s42
	v_cmp_gt_i32_e32 vcc, s30, v126
	v_lshl_add_u64 v[124:125], v[192:193], 1, v[130:131]
	global_load_dwordx4 v[116:119], v[124:125], off
	v_cndmask_b32_e32 v48, v127, v143, vcc
	v_add_u32_e32 v48, v48, v126
	v_mad_i64_i32 v[166:167], s[30:31], v48, s20, v[128:129]
	s_movk_i32 s30, 0xf8
	s_nop 0
	global_load_dwordx4 v[112:115], v[166:167], off
	s_nop 0
	v_lshl_add_u64 v[166:167], v[166:167], 0, s[100:101]
	global_load_dwordx4 v[120:123], v[166:167], off
	s_waitcnt vmcnt(9)
	ds_write_b128 v139, v[84:87] offset:8192
	ds_write_b128 v140, v[80:83] offset:12800
	s_waitcnt vmcnt(8)
	ds_write_b128 v139, v[88:91] offset:9344
	s_waitcnt vmcnt(7)
	ds_write_b128 v140, v[92:95] offset:14080
	s_waitcnt vmcnt(6)
	ds_write_b128 v139, v[96:99] offset:10496
	s_waitcnt vmcnt(5)
	ds_write_b128 v140, v[100:103] offset:15360
	s_waitcnt vmcnt(4)
	ds_write_b128 v139, v[104:107] offset:11648
	s_waitcnt vmcnt(3)
	ds_write_b128 v140, v[108:111] offset:16640
	ds_read_b128 v[80:83], v141 offset:8192
	ds_read_b128 v[84:87], v141 offset:8224
	v_add_co_u32_e32 v48, vcc, s89, v124
	s_movk_i32 s30, 0xf0
	s_nop 0
	v_addc_co_u32_e32 v49, vcc, 0, v125, vcc
	global_load_dwordx4 v[92:95], v[48:49], off
	ds_read_b128 v[146:149], v141 offset:8288
	v_lshl_add_u64 v[166:167], v[166:167], 0, s[100:101]
	global_load_dwordx4 v[96:99], v[166:167], off
	s_waitcnt lgkmcnt(2)
	v_mfma_f32_32x32x16_bf16 v[48:63], v[80:83], v[72:75], v[32:47]
	v_add_co_u32_e32 v80, vcc, s48, v124
	s_movk_i32 s30, 0xe8
	s_nop 0
	v_addc_co_u32_e32 v81, vcc, 0, v125, vcc
	global_load_dwordx4 v[100:103], v[80:81], off
	s_waitcnt lgkmcnt(1)
	v_mfma_f32_32x32x16_bf16 v[48:63], v[84:87], v[64:67], v[48:63]
	v_lshl_add_u64 v[166:167], v[166:167], 0, s[100:101]
	global_load_dwordx4 v[104:107], v[166:167], off
	v_add_co_u32_e32 v84, vcc, s49, v124
	ds_read_b128 v[80:83], v141 offset:8256
	s_nop 0
	v_addc_co_u32_e32 v85, vcc, 0, v125, vcc
	global_load_dwordx4 v[108:111], v[84:85], off
	s_waitcnt lgkmcnt(0)
	v_mfma_f32_32x32x16_bf16 v[48:63], v[80:83], v[68:71], v[48:63]
	ds_read_b128 v[88:91], v142 offset:12800
	ds_read_b128 v[80:83], v142 offset:12832
	ds_read_b128 v[124:127], v142 offset:15360
	ds_read_b128 v[84:87], v142 offset:15392
	s_and_b64 vcc, exec, s[28:29]
	v_mfma_f32_32x32x16_bf16 v[48:63], v[146:149], v[76:79], v[48:63]
	s_cbranch_vccz .LBB0_375
	s_add_i32 s30, s43, -8
	s_lshr_b32 s30, s30, 1
	v_add_u32_e32 v143, s30, v137
	s_movk_i32 s30, 0x7c
	v_mad_u64_u32 v[146:147], s[30:31], v143, s30, v[132:133]
	v_lshl_add_u32 v147, v135, 2, v146
	ds_read_b32 v168, v147 offset:928
	ds_read_b32 v169, v147 offset:932
	ds_read_b32 v170, v147 offset:936
	ds_read_b32 v171, v147 offset:940
	ds_read_b32 v172, v147 offset:944
	ds_read_b32 v173, v147 offset:948
	ds_read_b32 v174, v147 offset:952
	ds_read_b32 v175, v147 offset:956
	ds_read_b32 v176, v147 offset:992
	ds_read_b32 v177, v147 offset:996
	ds_read_b32 v178, v147 offset:1000
	ds_read_b32 v180, v147 offset:1004
	ds_read_b32 v182, v147 offset:1008
	ds_read_b32 v183, v147 offset:1012
	ds_read_b32 v184, v147 offset:1016
	ds_read_b32 v185, v147 offset:1020
	s_waitcnt lgkmcnt(0)
	v_readlane_b32 s44, v255, 12
	v_readlane_b32 s45, v255, 13
	v_add_f32_e32 v168, v48, v168
	s_nop 0
	v_cndmask_b32_e64 v146, v237, v168, s[44:45]
	v_readlane_b32 s44, v255, 14
	v_readlane_b32 s45, v255, 15
	v_add_f32_e32 v169, v49, v169
	s_nop 0
	v_cndmask_b32_e64 v143, v237, v169, s[44:45]
	v_readlane_b32 s44, v255, 16
	v_readlane_b32 s45, v255, 17
	v_add_f32_e32 v170, v50, v170
	s_nop 0
	v_cndmask_b32_e64 v148, v237, v170, s[44:45]
	v_readlane_b32 s44, v255, 18
	v_readlane_b32 s45, v255, 19
	v_add_f32_e32 v171, v51, v171
	s_nop 0
	v_cndmask_b32_e64 v149, v237, v171, s[44:45]
	v_readlane_b32 s44, v255, 20
	v_readlane_b32 s45, v255, 21
	v_add_f32_e32 v172, v52, v172
	s_nop 0
	v_cndmask_b32_e64 v159, v237, v172, s[44:45]
	v_readlane_b32 s44, v255, 22
	v_readlane_b32 s45, v255, 23
	v_add_f32_e32 v173, v53, v173
	s_nop 0
	v_cndmask_b32_e64 v160, v237, v173, s[44:45]
	v_add_f32_e32 v174, v54, v174
	s_nop 0
	v_cndmask_b32_e64 v161, v237, v174, s[50:51]
	v_add_f32_e32 v175, v55, v175
	s_nop 0
	v_cndmask_b32_e64 v162, v237, v175, s[52:53]
	v_add_f32_e32 v176, v56, v176
	s_nop 0
	v_cndmask_b32_e64 v163, v237, v176, s[46:47]
	v_add_f32_e32 v177, v57, v177
	s_nop 0
	v_cndmask_b32_e64 v151, v237, v177, s[0:1]
	v_add_f32_e32 v178, v58, v178
	s_nop 0
	v_cndmask_b32_e64 v150, v237, v178, s[90:91]
	v_add_f32_e32 v180, v59, v180
	s_nop 0
	v_cndmask_b32_e64 v157, v237, v180, s[92:93]
	v_add_f32_e32 v182, v60, v182
	s_nop 0
	v_cndmask_b32_e64 v156, v237, v182, s[94:95]
	v_add_f32_e32 v183, v61, v183
	s_nop 0
	v_cndmask_b32_e64 v158, v237, v183, s[26:27]
	v_add_f32_e32 v184, v62, v184
	s_nop 0
	v_cndmask_b32_e64 v165, v237, v184, s[24:25]
	v_add_f32_e32 v185, v63, v185
	s_nop 0
	v_cndmask_b32_e64 v164, v237, v185, s[72:73]
	v_exp_f32_e32 v158, v158
	v_exp_f32_e32 v156, v156
	v_exp_f32_e32 v157, v157
	v_exp_f32_e32 v150, v150
	v_exp_f32_e32 v151, v151
	v_exp_f32_e32 v147, v163
	v_exp_f32_e32 v163, v162
	v_exp_f32_e32 v161, v161
	v_exp_f32_e32 v162, v160
	v_exp_f32_e32 v159, v159
	v_exp_f32_e32 v160, v149
	v_exp_f32_e32 v148, v148
	v_exp_f32_e32 v149, v143
	v_exp_f32_e32 v143, v146
	v_exp_f32_e32 v146, v165
	s_branch .LBB0_377

; DI void frag64_load(Frag64& f, const bf16_t* P, const bf16_t* vt, int b, int u, int kcol, int lane) {
; #pragma unroll
;   for (int i = 0; i < 4; ++i) {
;     f.k[i] = *(const u32x4*)(P + (size_t)rowOfU(b, u + (lane >> 3) + 8 * i) * NP + kcol + (lane & 7) * 8);
;     f.v[i] = *(const u32x4*)(vt + (size_t)((lane >> 2) + 16 * i) * UA + u + (lane & 3) * 8);
;   }
; }
; template <int MODE>
; DI void attn64_wave(const Params& p, int layer, int b, int hq, int qrow0, int t0, const float* rpb_lds, unsigned char* wlds) {
;     ...
;   auto tile_u = [&](int t) -> int {
;     if (t < 8) return 32 * t;
;     if (MODE == 0) return CTX + (rs + ((t - 8) >> 1)) * 64 + ((t - 8) & 1) * 32;
;     const int kt0 = t0 - 128 + 32 * (t - 8);
;     return CTX + min(max(kt0, 0), SEQ - 32);
;   };
;   auto load_tile = [&](Frag64& f, int t) { frag64_load(f, p.P, vt, b, tile_u(t), kcol, lane); };
;   unsigned char* Kw = wlds; unsigned char* Vw = wlds + W64_KB;
;   auto compute_tile = [&](const Frag64& f, int t) {
; #pragma unroll
;     for (int i = 0; i < 4; ++i) {
;       *(u32x4*)(Kw + ((lane >> 3) + 8 * i) * LDS_STRIDE + (lane & 7) * 16) = f.k[i];
;       *(u32x4*)(Vw + ((lane >> 2) + 16 * i) * W64_VSTR + (lane & 3) * 16) = f.v[i];
;     }
;     bf16x8 kf[4], vf[2][2];
; #pragma unroll
;     for (int ks = 0; ks < 4; ++ks) kf[ks] = __builtin_bit_cast(bf16x8, *(const u32x4*)(Kw + pr * LDS_STRIDE + (16 * ks + 8 * hh) * 2));
; #pragma unroll
;     for (int dh = 0; dh < 2; ++dh)
; #pragma unroll
;       for (int s2 = 0; s2 < 2; ++s2) vf[dh][s2] = __builtin_bit_cast(bf16x8, *(const u32x4*)(Vw + (32 * dh + qi) * W64_VSTR + (16 * s2 + 8 * hh) * 2));
;     f32x16 s;
; #pragma unroll
;     for (int i = 0; i < 16; ++i) s[i] = negM2;
; #pragma unroll
;     for (int ks = 0; ks < 4; ++ks) s = MFMA32(kf[ks], qf[ks], s);
;     float pe[16];
;     if (t < 8) {
; #pragma unroll
;       for (int i = 0; i < 16; ++i) pe[i] = fexp2(s[i]);
;     } else if (MODE == 0) {
;       const int kr = rs + ((t - 8) >> 1), hf = (t - 8) & 1;
;       const float* rrow = rpb + (kr - r + 7) * 31 + 15 - c;
; #pragma unroll
;       for (int i = 0; i < 16; ++i) {
;         const int kc = hf * 32 + 16 * (i >> 3) + 8 * hh + (i & 7);
;         const bool valid = (kc >= ws) && (kc < ws + 16);
;         const int kcc = min(max(kc, ws), ws + 15);
;         pe[i] = fexp2(valid ? s[i] + rrow[kcc] : -1e30f);
;       }
.LBB0_381:
	v_add_u32_e32 v126, v48, v134
	s_movk_i32 s45, 0x100
	v_mov_b32_e32 v127, s22
	v_mov_b32_e32 v143, s42
	v_cmp_gt_i32_e32 vcc, s45, v126
	s_movk_i32 s45, 0xf8
	v_ashrrev_i32_e32 v49, 31, v48
	v_cndmask_b32_e32 v50, v127, v143, vcc
	v_add_u32_e32 v50, v50, v126
	v_mad_i64_i32 v[166:167], vcc, v50, s20, v[128:129]
	v_lshl_add_u64 v[124:125], v[48:49], 1, v[130:131]
	global_load_dwordx4 v[84:87], v[166:167], off
	v_lshl_add_u64 v[166:167], v[166:167], 0, s[100:101]
	global_load_dwordx4 v[80:83], v[124:125], off
	global_load_dwordx4 v[88:91], v[166:167], off
	s_waitcnt vmcnt(9)
	ds_write_b128 v139, v[112:115] offset:8192
	ds_write_b128 v140, v[116:119] offset:12800
	s_waitcnt vmcnt(8)
	ds_write_b128 v139, v[120:123] offset:9344
	s_waitcnt vmcnt(7)
	ds_write_b128 v140, v[92:95] offset:14080
	s_waitcnt vmcnt(6)
	ds_write_b128 v139, v[96:99] offset:10496
	s_waitcnt vmcnt(5)
	ds_write_b128 v140, v[100:103] offset:15360
	s_waitcnt vmcnt(4)
	ds_write_b128 v139, v[104:107] offset:11648
	s_waitcnt vmcnt(3)
	ds_write_b128 v140, v[108:111] offset:16640
	ds_read_b128 v[100:103], v141 offset:8192
	ds_read_b128 v[104:107], v141 offset:8224
	v_add_co_u32_e32 v48, vcc, s89, v124
	s_movk_i32 s45, 0xf0
	s_nop 0
	v_addc_co_u32_e32 v49, vcc, 0, v125, vcc
	global_load_dwordx4 v[92:95], v[48:49], off
	s_movk_i32 s45, 0xe8
	v_lshl_add_u64 v[166:167], v[166:167], 0, s[100:101]
	global_load_dwordx4 v[96:99], v[166:167], off
	s_waitcnt lgkmcnt(1)
	v_mfma_f32_32x32x16_bf16 v[48:63], v[100:103], v[72:75], v[32:47]
	v_add_co_u32_e32 v100, vcc, s48, v124
	ds_read_b128 v[146:149], v141 offset:8288
	s_nop 0
	v_addc_co_u32_e32 v101, vcc, 0, v125, vcc
	global_load_dwordx4 v[100:103], v[100:101], off
	s_waitcnt lgkmcnt(1)
	v_mfma_f32_32x32x16_bf16 v[48:63], v[104:107], v[64:67], v[48:63]
	ds_read_b128 v[108:111], v141 offset:8256
	v_lshl_add_u64 v[166:167], v[166:167], 0, s[100:101]
	v_add_co_u32_e32 v112, vcc, s49, v124
	global_load_dwordx4 v[104:107], v[166:167], off
	s_nop 0
	v_addc_co_u32_e32 v113, vcc, 0, v125, vcc
	s_waitcnt lgkmcnt(0)
	v_mfma_f32_32x32x16_bf16 v[48:63], v[108:111], v[68:71], v[48:63]
	global_load_dwordx4 v[108:111], v[112:113], off
	ds_read_b128 v[120:123], v142 offset:12800
	ds_read_b128 v[112:115], v142 offset:12832
	ds_read_b128 v[124:127], v142 offset:15360
	ds_read_b128 v[116:119], v142 offset:15392
	s_and_b64 vcc, exec, s[28:29]
	v_mfma_f32_32x32x16_bf16 v[48:63], v[146:149], v[76:79], v[48:63]
	s_cbranch_vccz .LBB0_415
	s_add_i32 s28, s43, -7
	s_lshr_b32 s28, s28, 1
	v_add_u32_e32 v143, s28, v137
	s_movk_i32 s28, 0x7c
	v_mad_u64_u32 v[146:147], s[28:29], v143, s28, v[132:133]
	v_lshl_add_u32 v147, v135, 2, v146
	ds_read_b32 v168, v147 offset:1056
	ds_read_b32 v169, v147 offset:1060
	ds_read_b32 v170, v147 offset:1064
	ds_read_b32 v171, v147 offset:1068
	ds_read_b32 v172, v147 offset:1072
	ds_read_b32 v173, v147 offset:1076
	ds_read_b32 v174, v147 offset:1080
	ds_read_b32 v175, v147 offset:1084
	ds_read_b32 v176, v147 offset:1120
	ds_read_b32 v177, v147 offset:1124
	ds_read_b32 v178, v147 offset:1128
	ds_read_b32 v180, v147 offset:1132
	ds_read_b32 v182, v147 offset:1136
	ds_read_b32 v183, v147 offset:1140
	ds_read_b32 v184, v147 offset:1144
	ds_read_b32 v185, v147 offset:1148
	s_waitcnt lgkmcnt(0)
	v_add_f32_e32 v168, v48, v168
	s_nop 0
	v_cndmask_b32_e64 v146, v237, v168, s[74:75]
	v_add_f32_e32 v169, v49, v169
	s_nop 0
	v_cndmask_b32_e64 v143, v237, v169, s[76:77]
	v_add_f32_e32 v170, v50, v170
	s_nop 0
	v_cndmask_b32_e64 v148, v237, v170, s[78:79]
	v_add_f32_e32 v171, v51, v171
	s_nop 0
	v_cndmask_b32_e64 v149, v237, v171, s[80:81]
	v_add_f32_e32 v172, v52, v172
	s_nop 0
	v_cndmask_b32_e64 v150, v237, v172, s[82:83]
	v_add_f32_e32 v173, v53, v173
	s_nop 0
	v_cndmask_b32_e64 v151, v237, v173, s[84:85]
	v_add_f32_e32 v174, v54, v174
	s_nop 0
	v_cndmask_b32_e64 v161, v237, v174, s[86:87]
	v_add_f32_e32 v175, v55, v175
	s_nop 0
	v_cndmask_b32_e64 v162, v237, v175, s[2:3]
	v_add_f32_e32 v176, v56, v176
	s_nop 0
	v_cndmask_b32_e64 v163, v237, v176, s[54:55]
	v_add_f32_e32 v177, v57, v177
	s_nop 0
	v_cndmask_b32_e64 v157, v237, v177, s[56:57]
	v_add_f32_e32 v178, v58, v178
	s_nop 0
	v_cndmask_b32_e64 v156, v237, v178, s[58:59]
	v_add_f32_e32 v180, v59, v180
	s_nop 0
	v_cndmask_b32_e64 v159, v237, v180, s[60:61]
	v_add_f32_e32 v182, v60, v182
	s_nop 0
	v_cndmask_b32_e64 v158, v237, v182, s[62:63]
	v_add_f32_e32 v183, v61, v183
	s_nop 0
	v_cndmask_b32_e64 v160, v237, v183, s[64:65]
	v_add_f32_e32 v184, v62, v184
	s_nop 0
	v_cndmask_b32_e64 v165, v237, v184, s[66:67]
	v_add_f32_e32 v185, v63, v185
	s_nop 0
	v_cndmask_b32_e64 v164, v237, v185, s[68:69]
	v_exp_f32_e32 v160, v160
	v_exp_f32_e32 v158, v158
	v_exp_f32_e32 v159, v159
	v_exp_f32_e32 v156, v156
	v_exp_f32_e32 v157, v157
	v_exp_f32_e32 v147, v163
	v_exp_f32_e32 v163, v162
	v_exp_f32_e32 v161, v161
	v_exp_f32_e32 v162, v151
	v_exp_f32_e32 v150, v150
	v_exp_f32_e32 v151, v149
	v_exp_f32_e32 v148, v148
	v_exp_f32_e32 v149, v143
	v_exp_f32_e32 v143, v146
	v_exp_f32_e32 v146, v165
	s_branch .LBB0_338
